# static s_setprio 1 for waves 4-7 during the attention phase (reset to 0 at its end); otherwise v19
# speedup vs baseline: 1.0087x; 1.0087x over previous
; #define LAUNDER_TID() int tid = tid0; asm volatile("" : "+v"(tid)); const int lane = tid & 63
; #define GRID_SYNC() do { xcd_barrier(xbar); } while (0)
; #define GRID_SYNC() do { xcd_barrier(xbar); } while (0)
; __global__ void __launch_bounds__(NTHR, 2) fwd_megakernel(Args args) {
;     ...
;         for (int rep_ = 0; rep_ < REP_P2; ++rep_) {
;             if (rep_) GRID_SYNC();
;             LAUNDER_TID();
;             using abf = att::bf16; typedef att::BlockRef<abf, abf> BR;
;             char* al = (char*)lds; float* csl = (float*)((char*)lds + att::LDS_BYTES);
;             const abf* Qb = (const abf*)Z + 3 * CWD; const abf* Kb = (const abf*)Z + 4 * CWD;
;             constexpr int NQB = S / att::QB, NITEM = NH * (NQB / 2);
;             unsigned ord = 0u;
;             {   float ce[NH];
; #pragma unroll
;                 for (int h = 0; h < NH; ++h) ce[h] = cs[(size_t)h * S + S - 1];
; #pragma unroll
;                 for (int hh = 0; hh < NH; ++hh) { int rr = 0;
; #pragma unroll
;                     for (int g2 = 0; g2 < NH; ++g2) rr += (ce[g2] > ce[hh] || (ce[g2] == ce[hh] && g2 < hh)) ? 1 : 0;
;                     ord |= (unsigned)hh << (4 * rr); }
;                 ord = __builtin_amdgcn_readfirstlane(ord); }
.LBB0_296:
	s_or_b64 exec, exec, s[14:15]
	s_waitcnt lgkmcnt(0)
	v_readfirstlane_b32 s16, v202
	s_nop 3
	s_cmpk_ge_u32 s16, 0x100
	s_cbranch_scc0 .Lattn_prio_done
	s_setprio 1
.Lattn_prio_done:
	v_mov_b32_e32 v0, v202
	v_readlane_b32 s14, v253, 60
	s_barrier
	v_readlane_b32 s15, v253, 61
	s_lshl_b32 s86, s28, 6
	s_lshl_b64 s[50:51], s[28:29], 11
	v_readlane_b32 s16, v253, 49
	s_mov_b64 s[52:53], 0
	v_readlane_b32 s17, v254, 12
	global_load_dword v0, v193, s[14:15]
	v_readlane_b32 s14, v253, 62
	v_readlane_b32 s15, v253, 63
	s_nop 4
	global_load_dword v1, v193, s[14:15]
	v_readlane_b32 s14, v254, 0
	v_readlane_b32 s15, v254, 1
	s_waitcnt vmcnt(0)
	v_cmp_ge_f32_e32 vcc, v0, v1
	s_nop 2
	global_load_dword v2, v193, s[14:15]
	v_readlane_b32 s14, v254, 4
	v_readlane_b32 s15, v254, 5
	v_cndmask_b32_e64 v8, 0, 1, vcc
	s_waitcnt vmcnt(0)
	v_cmp_gt_f32_e32 vcc, v2, v1
	s_nop 1
	global_load_dword v3, v193, s[14:15]
	v_readlane_b32 s14, v254, 8
	v_readlane_b32 s15, v254, 9
	v_cndmask_b32_e64 v9, 0, 1, vcc
	s_waitcnt vmcnt(0)
	v_cmp_gt_f32_e32 vcc, v3, v1
	s_nop 1
	global_load_dword v4, v193, s[14:15]
	v_readlane_b32 s14, v254, 10
	v_readlane_b32 s15, v254, 11
	v_cndmask_b32_e64 v10, 0, 1, vcc
	s_waitcnt vmcnt(0)
	v_cmp_gt_f32_e32 vcc, v4, v1
	s_nop 1
	global_load_dword v5, v193, s[14:15]
	v_readlane_b32 s14, v254, 6
	v_readlane_b32 s15, v254, 7
	v_cndmask_b32_e64 v11, 0, 1, vcc
	v_cmp_ge_f32_e32 vcc, v0, v2
	s_nop 1
	v_cndmask_b32_e64 v12, 0, 1, vcc
	global_load_dword v6, v193, s[14:15]
	v_readlane_b32 s14, v254, 2
	v_readlane_b32 s15, v254, 3
	v_cmp_ge_f32_e32 vcc, v1, v2
	s_nop 1
	v_cndmask_b32_e64 v13, 0, 1, vcc
	v_cmp_gt_f32_e32 vcc, v3, v2
	global_load_dword v7, v193, s[14:15]
	s_lshl_b64 s[14:15], s[86:87], 2
	v_cndmask_b32_e64 v14, 0, 1, vcc
	v_cmp_gt_f32_e32 vcc, v4, v2
	s_add_u32 s46, s16, s14
	v_readlane_b32 s14, v253, 50
	v_cndmask_b32_e64 v15, 0, 1, vcc
	s_addc_u32 s47, s14, s15
	s_waitcnt vmcnt(0)
	v_cmp_ge_f32_e32 vcc, v0, v7
	s_nop 1
	v_cndmask_b32_e64 v16, 0, 1, vcc
	v_cmp_ge_f32_e32 vcc, v1, v7
	s_nop 1
	v_cndmask_b32_e64 v17, 0, 1, vcc
	v_cmp_gt_f32_e32 vcc, v3, v7
	s_nop 1
	v_cndmask_b32_e64 v18, 0, 1, vcc
	v_cmp_gt_f32_e32 vcc, v4, v7
	s_nop 1
	v_cndmask_b32_e64 v19, 0, 1, vcc
	v_cmp_ge_f32_e32 vcc, v0, v3
	s_nop 1
	v_cndmask_b32_e64 v20, 0, 1, vcc
	v_cmp_ge_f32_e32 vcc, v1, v3
	s_nop 1
	v_cndmask_b32_e64 v21, 0, 1, vcc
	v_cmp_ge_f32_e32 vcc, v7, v3
	s_nop 1
	v_cndmask_b32_e64 v22, 0, 1, vcc
	v_cmp_gt_f32_e32 vcc, v7, v1
	s_nop 1
	v_addc_co_u32_e32 v8, vcc, v8, v9, vcc
	v_cmp_gt_f32_e32 vcc, v7, v2
	s_nop 1
	v_addc_co_u32_e32 v9, vcc, v12, v13, vcc
	v_cmp_ge_f32_e32 vcc, v2, v7
	s_nop 1
	v_addc_co_u32_e32 v12, vcc, v16, v17, vcc
	v_cmp_ge_f32_e32 vcc, v2, v3
	s_nop 1
	v_addc_co_u32_e32 v13, vcc, v20, v21, vcc
	v_cmp_gt_f32_e32 vcc, v6, v1
	s_nop 1
	v_addc_co_u32_e32 v8, vcc, v8, v10, vcc
	v_cmp_gt_f32_e32 vcc, v6, v2
	s_nop 1
	v_addc_co_u32_e32 v9, vcc, v9, v14, vcc
	v_cmp_gt_f32_e32 vcc, v6, v7
	s_nop 1
	v_addc_co_u32_e32 v10, vcc, v12, v18, vcc
	v_cmp_gt_f32_e32 vcc, v6, v3
	s_nop 1
	v_addc_co_u32_e32 v12, vcc, v13, v22, vcc
	v_cmp_gt_f32_e32 vcc, v5, v1
	s_nop 1
	v_addc_co_u32_e32 v8, vcc, v8, v11, vcc
	v_cmp_gt_f32_e32 vcc, v5, v2
	v_lshlrev_b32_e32 v8, 2, v8
	v_lshlrev_b32_e64 v8, v8, 1
	v_addc_co_u32_e32 v9, vcc, v9, v15, vcc
	v_cmp_gt_f32_e32 vcc, v5, v7
	v_lshlrev_b32_e32 v9, 2, v9
	v_lshlrev_b32_e64 v9, v9, 2
	v_addc_co_u32_e32 v10, vcc, v10, v19, vcc
	v_cmp_gt_f32_e32 vcc, v4, v3
	v_or_b32_e32 v8, v9, v8
	v_lshlrev_b32_e32 v10, 2, v10
	v_cndmask_b32_e64 v9, 0, 1, vcc
	v_cmp_gt_f32_e32 vcc, v5, v3
	v_lshlrev_b32_e64 v10, v10, 3
	v_or_b32_e32 v8, v10, v8
	v_addc_co_u32_e32 v9, vcc, v12, v9, vcc
	v_lshlrev_b32_e32 v9, 2, v9
	v_lshlrev_b32_e64 v9, v9, 4
	v_cmp_ge_f32_e32 vcc, v0, v6
	v_or_b32_e32 v8, v9, v8
	s_nop 0
	v_cndmask_b32_e64 v9, 0, 1, vcc
	v_cmp_ge_f32_e32 vcc, v1, v6
	s_nop 1
	v_cndmask_b32_e64 v10, 0, 1, vcc
	v_cmp_ge_f32_e32 vcc, v2, v6
	s_nop 1
	v_addc_co_u32_e32 v9, vcc, v9, v10, vcc
	v_cmp_ge_f32_e32 vcc, v7, v6
	s_nop 1
	v_cndmask_b32_e64 v10, 0, 1, vcc
	v_cmp_ge_f32_e32 vcc, v3, v6
	s_nop 1
	v_addc_co_u32_e32 v9, vcc, v9, v10, vcc
	v_cmp_gt_f32_e32 vcc, v4, v6
	s_nop 1
	v_cndmask_b32_e64 v10, 0, 1, vcc
	v_cmp_gt_f32_e32 vcc, v5, v6
	s_nop 1
	v_addc_co_u32_e32 v9, vcc, v9, v10, vcc
	v_lshlrev_b32_e32 v9, 2, v9
	v_lshlrev_b32_e64 v9, v9, 5
	v_cmp_ge_f32_e32 vcc, v0, v4
	v_or_b32_e32 v8, v9, v8
	s_nop 0
	v_cndmask_b32_e64 v9, 0, 1, vcc
	v_cmp_ge_f32_e32 vcc, v1, v4
	s_nop 1
	v_cndmask_b32_e64 v10, 0, 1, vcc
	v_cmp_ge_f32_e32 vcc, v2, v4
	s_nop 1
	v_addc_co_u32_e32 v9, vcc, v9, v10, vcc
	v_cmp_ge_f32_e32 vcc, v7, v4
	s_nop 1
	v_cndmask_b32_e64 v10, 0, 1, vcc
	v_cmp_ge_f32_e32 vcc, v3, v4
	s_nop 1
	v_addc_co_u32_e32 v9, vcc, v9, v10, vcc
	v_cmp_ge_f32_e32 vcc, v6, v4
	s_nop 1
	v_cndmask_b32_e64 v10, 0, 1, vcc
	v_cmp_gt_f32_e32 vcc, v5, v4
	s_nop 1
	v_addc_co_u32_e32 v9, vcc, v9, v10, vcc
	v_cmp_ge_f32_e32 vcc, v0, v5
	v_lshlrev_b32_e32 v9, 2, v9
	v_lshlrev_b32_e64 v9, v9, 6
	v_cndmask_b32_e64 v0, 0, 1, vcc
	v_cmp_ge_f32_e32 vcc, v1, v5
	v_or_b32_e32 v8, v9, v8
	s_nop 0
	v_cndmask_b32_e64 v1, 0, 1, vcc
	v_cmp_ge_f32_e32 vcc, v2, v5
	s_nop 1
	v_addc_co_u32_e32 v0, vcc, v0, v1, vcc
	v_cmp_ge_f32_e32 vcc, v7, v5
	s_nop 1
	v_cndmask_b32_e64 v1, 0, 1, vcc
	v_cmp_ge_f32_e32 vcc, v3, v5
	s_nop 1
	v_addc_co_u32_e32 v0, vcc, v0, v1, vcc
	v_cmp_ge_f32_e32 vcc, v6, v5
	s_nop 1
	v_cndmask_b32_e64 v1, 0, 1, vcc
	v_cmp_ge_f32_e32 vcc, v4, v5
	s_nop 1
	v_addc_co_u32_e32 v0, vcc, v0, v1, vcc
	v_lshlrev_b32_e32 v0, 2, v0
	v_lshlrev_b32_e64 v0, v0, 7
	v_or_b32_e32 v0, v0, v8
	s_nop 0
	v_readfirstlane_b32 s54, v0
	s_branch .LBB0_299

; __device__ __forceinline__ void xcd_barrier(const XcdBarrier& b) {
;     asm volatile("s_waitcnt vmcnt(0)" ::: "memory");
;     __syncthreads();
;     if (threadIdx.x == 0) {
;         unsigned* bar = b.bar;
;         __builtin_amdgcn_s_waitcnt(0);
;         unsigned nloc = b.st[0], nx = b.st[1];
;         if (nloc == 0u) { xcd_barrier_complete(bar, b.x, nloc, nx); b.st[0] = nloc; b.st[1] = nx; }
.LBB0_527:
	s_setprio 0
	s_waitcnt vmcnt(0)
	s_barrier
	s_and_saveexec_b64 s[14:15], s[56:57]
	s_cbranch_execz .LBB0_579
	v_readlane_b32 s16, v255, 41
	s_waitcnt vmcnt(0) expcnt(0) lgkmcnt(0)
	s_nop 0
	v_mov_b32_e32 v0, s16
	ds_read_b32 v2, v0
	v_readlane_b32 s16, v255, 42
	s_waitcnt lgkmcnt(0)
	v_cmp_ne_u32_e32 vcc, 0, v2
	v_mov_b32_e32 v0, s16
	ds_read_b32 v0, v0
	s_cbranch_vccnz .LBB0_543
	s_mov_b32 s16, 1
	s_branch .LBB0_531
